# out-projection epilogue: waves 0-3 (which publish and gather the row statistics) fetch their residual rows after the first exchange so the exchange no longer waits behind the residual-row load burst
# baseline (speedup 1.0000x reference)
.LBB0_1269:
	v_readlane_b32 s86, v255, 6
	v_readlane_b32 s87, v255, 7
	v_readlane_b32 s80, v255, 0
	s_lshl_b64 s[4:5], s[86:87], 13
	v_readlane_b32 s82, v255, 2
	v_readlane_b32 s83, v255, 3
	s_add_u32 s4, s82, s4
	s_addc_u32 s5, s83, s5
	s_lshl_b32 s6, s46, 5
	s_lshl_b32 s7, s84, 8
	s_or_b32 s6, s7, s6
	v_lshl_or_b32 v212, v215, 2, s6
	v_ashrrev_i32_e32 v213, 31, v212
	v_lshlrev_b64 v[144:145], 2, v[212:213]
	s_lshl_b32 s13, s26, 8
	v_lshl_add_u64 v[128:129], s[4:5], 0, v[144:145]
	s_add_i32 s4, s13, s47
	v_or_b32_e32 v146, s4, v214
	v_readlane_b32 s4, v254, 60
	v_readlane_b32 s5, v254, 61
	v_ashrrev_i32_e32 v147, 31, v146
	s_waitcnt vmcnt(0)
	s_barrier
	v_lshl_add_u64 v[216:217], s[4:5], 0, v[144:145]
	v_readfirstlane_b32 s32, v226
	s_cmpk_lt_u32 s32, 0x100
	s_cbranch_scc1 .Lx_top_skip
	v_lshlrev_b64 v[144:145], 13, v[146:147]
	v_lshl_add_u64 v[144:145], v[216:217], 0, v[144:145]
	global_load_dwordx4 v[140:143], v[128:129], off
	global_load_dwordx4 v[136:139], v[128:129], off offset:64
	global_load_dwordx4 v[132:135], v[128:129], off offset:512
	s_nop 0
	global_load_dwordx4 v[128:131], v[128:129], off offset:576
	s_nop 0
	global_load_dwordx4 v[204:207], v[144:145], off
	global_load_dwordx4 v[200:203], v[144:145], off offset:64
	global_load_dwordx4 v[196:199], v[144:145], off offset:512
	global_load_dwordx4 v[192:195], v[144:145], off offset:576
	v_or_b32_e32 v144, 16, v146
	v_ashrrev_i32_e32 v145, 31, v144
	v_lshlrev_b64 v[144:145], 13, v[144:145]
	v_lshl_add_u64 v[144:145], v[216:217], 0, v[144:145]
	global_load_dwordx4 v[188:191], v[144:145], off
	global_load_dwordx4 v[184:187], v[144:145], off offset:64
	global_load_dwordx4 v[180:183], v[144:145], off offset:512
	global_load_dwordx4 v[176:179], v[144:145], off offset:576
	v_or_b32_e32 v144, 32, v146
	v_ashrrev_i32_e32 v145, 31, v144
	v_lshlrev_b64 v[144:145], 13, v[144:145]
	v_lshl_add_u64 v[144:145], v[216:217], 0, v[144:145]
	global_load_dwordx4 v[172:175], v[144:145], off
	global_load_dwordx4 v[168:171], v[144:145], off offset:64
	global_load_dwordx4 v[164:167], v[144:145], off offset:512
	global_load_dwordx4 v[160:163], v[144:145], off offset:576
	v_or_b32_e32 v144, 48, v146
	v_ashrrev_i32_e32 v145, 31, v144
	v_lshlrev_b64 v[144:145], 13, v[144:145]
	v_lshl_add_u64 v[144:145], v[216:217], 0, v[144:145]
	global_load_dwordx4 v[156:159], v[144:145], off
	global_load_dwordx4 v[152:155], v[144:145], off offset:64
	global_load_dwordx4 v[148:151], v[144:145], off offset:512
	s_nop 0
	global_load_dwordx4 v[144:147], v[144:145], off offset:576
.Lx_top_skip:
	v_and_b32_e32 v218, 64, v233
	v_xor_b32_e32 v208, 16, v233
	v_add_u32_e32 v218, 64, v218
	v_cmp_lt_i32_e32 vcc, v208, v218
	v_cmp_eq_u32_e64 s[4:5], 0, v215
	v_mul_f32_e32 v215, v125, v125
	v_cndmask_b32_e32 v208, v233, v208, vcc
	v_lshlrev_b32_e32 v248, 2, v208
	v_xor_b32_e32 v208, 32, v233
	v_cmp_lt_i32_e32 vcc, v208, v218
	v_mul_f32_e32 v218, v127, v127
	v_fmac_f32_e32 v215, v124, v124
	v_fmac_f32_e32 v218, v126, v126
	v_add_f32_e32 v215, v215, v218
	v_mul_f32_e32 v218, v121, v121
	v_mul_f32_e32 v219, v123, v123
	v_fmac_f32_e32 v218, v120, v120
	v_fmac_f32_e32 v219, v122, v122
	v_add_f32_e32 v218, v218, v219
	v_add_f32_e32 v215, v218, v215
	v_mul_f32_e32 v218, v117, v117
	v_mul_f32_e32 v219, v119, v119
	v_fmac_f32_e32 v218, v116, v116
	v_fmac_f32_e32 v219, v118, v118
	v_add_f32_e32 v218, v218, v219
	v_add_f32_e32 v215, v218, v215
	v_mul_f32_e32 v218, v113, v113
	v_mul_f32_e32 v219, v115, v115
	v_fmac_f32_e32 v218, v112, v112
	v_fmac_f32_e32 v219, v114, v114
	v_add_f32_e32 v218, v218, v219
	v_add_f32_e32 v215, v218, v215
	ds_bpermute_b32 v218, v248, v215
	v_cndmask_b32_e32 v208, v233, v208, vcc
	v_lshlrev_b32_e32 v208, 2, v208
	s_lshl_b32 s6, s46, 2
	v_readlane_b32 s81, v255, 1
	s_waitcnt lgkmcnt(0)
	v_add_f32_e32 v215, v215, v218
	ds_bpermute_b32 v218, v208, v215
	s_add_i32 s12, s6, 0
	s_and_saveexec_b64 s[6:7], s[4:5]
	s_cbranch_execz .LBB0_1271
	s_lshl_b32 s8, s31, 10
	s_add_i32 s8, s12, s8
	s_waitcnt lgkmcnt(0)
	v_add_f32_e32 v215, v215, v218
	v_lshl_add_u32 v218, v214, 4, s8
	ds_write_b32 v218, v215

.LBB0_1287:
	s_or_b64 exec, exec, s[8:9]
	s_lshl_b64 s[8:9], s[86:87], 11
	s_add_u32 s8, s56, s8
	s_addc_u32 s9, s57, s9
	s_cmpk_gt_u32 s32, 0xff
	s_cbranch_scc1 .Lx_nowait
	s_waitcnt vmcnt(0)
.Lx_nowait:
	s_barrier
	s_add_u32 s43, s8, 0x1a880000
	s_addc_u32 s44, s9, 0
	v_cmp_eq_u32_e64 s[8:9], 0, v246
	s_and_saveexec_b64 s[22:23], s[8:9]
	s_cbranch_execz .LBB0_1299
	s_lshl_b32 s38, s26, 4
	s_mov_b64 s[30:31], exec
	s_ashr_i32 s39, s38, 31
	s_lshl_b64 s[38:39], s[38:39], 2
	s_waitcnt lgkmcnt(0)
	v_mbcnt_lo_u32_b32 v218, s30, 0
	s_add_u32 s38, s43, s38
	v_mbcnt_hi_u32_b32 v218, s31, v218
	s_addc_u32 s39, s44, s39
	v_cmp_eq_u32_e32 vcc, 0, v218
	s_and_saveexec_b64 s[40:41], vcc
	s_cbranch_execz .LBB0_1290
	s_bcnt1_i32_b64 s30, s[30:31]
	v_mov_b32_e32 v218, s30
	global_atomic_add v209, v218, s[38:39]

.LBB0_1301:
	s_or_b64 exec, exec, s[22:23]
	s_cmpk_gt_u32 s32, 0xff
	s_cbranch_scc1 .Lx_ld_done
	v_lshlrev_b64 v[144:145], 13, v[146:147]
	v_lshl_add_u64 v[144:145], v[216:217], 0, v[144:145]
	global_load_dwordx4 v[140:143], v[128:129], off
	global_load_dwordx4 v[136:139], v[128:129], off offset:64
	global_load_dwordx4 v[132:135], v[128:129], off offset:512
	s_nop 0
	global_load_dwordx4 v[128:131], v[128:129], off offset:576
	s_nop 0
	global_load_dwordx4 v[204:207], v[144:145], off
	global_load_dwordx4 v[200:203], v[144:145], off offset:64
	global_load_dwordx4 v[196:199], v[144:145], off offset:512
	global_load_dwordx4 v[192:195], v[144:145], off offset:576
	v_or_b32_e32 v144, 16, v146
	v_ashrrev_i32_e32 v145, 31, v144
	v_lshlrev_b64 v[144:145], 13, v[144:145]
	v_lshl_add_u64 v[144:145], v[216:217], 0, v[144:145]
	global_load_dwordx4 v[188:191], v[144:145], off
	global_load_dwordx4 v[184:187], v[144:145], off offset:64
	global_load_dwordx4 v[180:183], v[144:145], off offset:512
	global_load_dwordx4 v[176:179], v[144:145], off offset:576
	v_or_b32_e32 v144, 32, v146
	v_ashrrev_i32_e32 v145, 31, v144
	v_lshlrev_b64 v[144:145], 13, v[144:145]
	v_lshl_add_u64 v[144:145], v[216:217], 0, v[144:145]
	global_load_dwordx4 v[172:175], v[144:145], off
	global_load_dwordx4 v[168:171], v[144:145], off offset:64
	global_load_dwordx4 v[164:167], v[144:145], off offset:512
	global_load_dwordx4 v[160:163], v[144:145], off offset:576
	v_or_b32_e32 v144, 48, v146
	v_ashrrev_i32_e32 v145, 31, v144
	v_lshlrev_b64 v[144:145], 13, v[144:145]
	v_lshl_add_u64 v[144:145], v[216:217], 0, v[144:145]
	global_load_dwordx4 v[156:159], v[144:145], off
	global_load_dwordx4 v[152:155], v[144:145], off offset:64
	global_load_dwordx4 v[148:151], v[144:145], off offset:512
	s_nop 0
	global_load_dwordx4 v[144:147], v[144:145], off offset:576
.Lx_ld_done:
	s_waitcnt lgkmcnt(0)
	s_barrier
	v_lshl_add_u32 v249, v247, 2, 0
	s_waitcnt lgkmcnt(0)
	ds_read_b32 v218, v249 offset:4096
	v_add_u32_e32 v224, s13, v247
	v_ashrrev_i32_e32 v225, 31, v224
	v_lshlrev_b64 v[220:221], 11, v[224:225]
	v_readlane_b32 s30, v254, 62
	s_waitcnt lgkmcnt(0)
	v_pk_mul_f32 v[112:113], v[112:113], v[218:219] op_sel_hi:[1,0]
	v_lshl_add_u64 v[220:221], v[220:221], 0, v[212:213]
	s_waitcnt vmcnt(0)
	v_pk_fma_f32 v[112:113], v[128:129], v[112:113], v[192:193]
	v_lshlrev_b64 v[192:193], 13, v[224:225]
	v_pk_mul_f32 v[124:125], v[124:125], v[218:219] op_sel_hi:[1,0]
	v_pk_mul_f32 v[126:127], v[126:127], v[218:219] op_sel_hi:[1,0]
	v_readlane_b32 s31, v254, 63
	v_pk_mul_f32 v[120:121], v[120:121], v[218:219] op_sel_hi:[1,0]
	v_pk_mul_f32 v[122:123], v[122:123], v[218:219] op_sel_hi:[1,0]
	v_pk_mul_f32 v[116:117], v[116:117], v[218:219] op_sel_hi:[1,0]
	v_pk_mul_f32 v[118:119], v[118:119], v[218:219] op_sel_hi:[1,0]
	v_pk_mul_f32 v[114:115], v[114:115], v[218:219] op_sel_hi:[1,0]
	v_lshl_add_u64 v[192:193], v[216:217], 0, v[192:193]
	v_pk_fma_f32 v[126:127], v[142:143], v[126:127], v[206:207]
	v_pk_fma_f32 v[124:125], v[140:141], v[124:125], v[204:205]
	v_lshl_add_u64 v[204:205], v[220:221], 2, s[30:31]
	v_pk_fma_f32 v[122:123], v[138:139], v[122:123], v[202:203]
	v_pk_fma_f32 v[120:121], v[136:137], v[120:121], v[200:201]
	v_pk_fma_f32 v[118:119], v[134:135], v[118:119], v[198:199]
	v_pk_fma_f32 v[116:117], v[132:133], v[116:117], v[196:197]
	v_pk_fma_f32 v[114:115], v[130:131], v[114:115], v[194:195]
	v_add_co_u32_e32 v192, vcc, 0x100000, v192
	global_store_dwordx4 v[204:205], v[124:127], off
	global_store_dwordx4 v[204:205], v[120:123], off offset:64
	global_store_dwordx4 v[204:205], v[116:119], off offset:512
	global_store_dwordx4 v[204:205], v[112:115], off offset:576
	v_addc_co_u32_e32 v193, vcc, 0, v193, vcc
	global_load_dwordx4 v[204:207], v[192:193], off
	global_load_dwordx4 v[200:203], v[192:193], off offset:64
	global_load_dwordx4 v[196:199], v[192:193], off offset:512
	s_nop 0
	global_load_dwordx4 v[192:195], v[192:193], off offset:576
	v_mul_f32_e32 v218, v125, v125
	v_mul_f32_e32 v219, v127, v127
	v_fmac_f32_e32 v218, v124, v124
	v_fmac_f32_e32 v219, v126, v126
	v_add_f32_e32 v218, v218, v219
	v_mul_f32_e32 v219, v121, v121
	v_mul_f32_e32 v220, v123, v123
	v_fmac_f32_e32 v219, v120, v120
	v_fmac_f32_e32 v220, v122, v122
	v_add_f32_e32 v219, v219, v220
	v_add_f32_e32 v218, v218, v219
	v_mul_f32_e32 v219, v117, v117
	v_mul_f32_e32 v220, v119, v119
	v_fmac_f32_e32 v219, v116, v116
	v_fmac_f32_e32 v220, v118, v118
	v_add_f32_e32 v219, v219, v220
	v_add_f32_e32 v218, v219, v218
	v_mul_f32_e32 v219, v113, v113
	v_mul_f32_e32 v220, v115, v115
	v_fmac_f32_e32 v219, v112, v112
	v_fmac_f32_e32 v220, v114, v114
	v_add_f32_e32 v219, v219, v220
	v_add_f32_e32 v218, v219, v218
	ds_bpermute_b32 v219, v248, v218
	s_waitcnt lgkmcnt(0)
	v_add_f32_e32 v218, v218, v219
	ds_bpermute_b32 v219, v208, v218
	s_and_saveexec_b64 s[14:15], s[4:5]
	s_cbranch_execz .LBB0_1303
	v_lshl_add_u32 v220, v247, 4, s12
	s_waitcnt lgkmcnt(0)
	v_add_f32_e32 v218, v218, v219
	ds_write_b32 v220, v218
